# all three GEMM instances: first K-iteration of every unit peeled with C=0 on the first MFMA of each accumulator, so the 128 (kind-2/split-K: 256) v_mov that cleared the accumulators per unit are gone
# speedup vs baseline: 1.0113x; 1.0034x over previous
.LBB0_475:
	v_readlane_b32 s38, v255, 16
	v_mov_b32_e32 v129, 0
	v_readlane_b32 s39, v255, 17
	s_andn2_b64 vcc, exec, s[38:39]
	s_cbranch_vccz .Lzp2_go
	v_mov_b32_e32 v128, v129
	v_mov_b32_e32 v127, v129
	v_mov_b32_e32 v126, v129
	v_mov_b32_e32 v125, v129
	v_mov_b32_e32 v124, v129
	v_mov_b32_e32 v123, v129
	v_mov_b32_e32 v122, v129
	v_mov_b32_e32 v111, v129
	v_mov_b32_e32 v110, v129
	v_mov_b32_e32 v109, v129
	v_mov_b32_e32 v108, v129
	v_mov_b32_e32 v107, v129
	v_mov_b32_e32 v106, v129
	v_mov_b32_e32 v105, v129
	v_mov_b32_e32 v104, v129
	v_mov_b32_e32 v95, v129
	v_mov_b32_e32 v94, v129
	v_mov_b32_e32 v93, v129
	v_mov_b32_e32 v92, v129
	v_mov_b32_e32 v91, v129
	v_mov_b32_e32 v90, v129
	v_mov_b32_e32 v89, v129
	v_mov_b32_e32 v88, v129
	v_mov_b32_e32 v79, v129
	v_mov_b32_e32 v78, v129
	v_mov_b32_e32 v77, v129
	v_mov_b32_e32 v76, v129
	v_mov_b32_e32 v75, v129
	v_mov_b32_e32 v74, v129
	v_mov_b32_e32 v73, v129
	v_mov_b32_e32 v72, v129
	v_mov_b32_e32 v121, v129
	v_mov_b32_e32 v120, v129
	v_mov_b32_e32 v119, v129
	v_mov_b32_e32 v118, v129
	v_mov_b32_e32 v117, v129
	v_mov_b32_e32 v116, v129
	v_mov_b32_e32 v115, v129
	v_mov_b32_e32 v114, v129
	v_mov_b32_e32 v103, v129
	v_mov_b32_e32 v102, v129
	v_mov_b32_e32 v101, v129
	v_mov_b32_e32 v100, v129
	v_mov_b32_e32 v99, v129
	v_mov_b32_e32 v98, v129
	v_mov_b32_e32 v97, v129
	v_mov_b32_e32 v96, v129
	v_mov_b32_e32 v87, v129
	v_mov_b32_e32 v86, v129
	v_mov_b32_e32 v85, v129
	v_mov_b32_e32 v84, v129
	v_mov_b32_e32 v83, v129
	v_mov_b32_e32 v82, v129
	v_mov_b32_e32 v81, v129
	v_mov_b32_e32 v80, v129
	v_mov_b32_e32 v71, v129
	v_mov_b32_e32 v70, v129
	v_mov_b32_e32 v69, v129
	v_mov_b32_e32 v68, v129
	v_mov_b32_e32 v67, v129
	v_mov_b32_e32 v66, v129
	v_mov_b32_e32 v65, v129
	v_mov_b32_e32 v64, v129
	v_mov_b32_e32 v63, v129
	v_mov_b32_e32 v62, v129
	v_mov_b32_e32 v61, v129
	v_mov_b32_e32 v60, v129
	v_mov_b32_e32 v59, v129
	v_mov_b32_e32 v58, v129
	v_mov_b32_e32 v57, v129
	v_mov_b32_e32 v56, v129
	v_mov_b32_e32 v47, v129
	v_mov_b32_e32 v46, v129
	v_mov_b32_e32 v45, v129
	v_mov_b32_e32 v44, v129
	v_mov_b32_e32 v43, v129
	v_mov_b32_e32 v42, v129
	v_mov_b32_e32 v41, v129
	v_mov_b32_e32 v40, v129
	v_mov_b32_e32 v31, v129
	v_mov_b32_e32 v30, v129
	v_mov_b32_e32 v29, v129
	v_mov_b32_e32 v28, v129
	v_mov_b32_e32 v27, v129
	v_mov_b32_e32 v26, v129
	v_mov_b32_e32 v25, v129
	v_mov_b32_e32 v24, v129
	v_mov_b32_e32 v15, v129
	v_mov_b32_e32 v14, v129
	v_mov_b32_e32 v13, v129
	v_mov_b32_e32 v12, v129
	v_mov_b32_e32 v11, v129
	v_mov_b32_e32 v10, v129
	v_mov_b32_e32 v9, v129
	v_mov_b32_e32 v8, v129
	v_mov_b32_e32 v55, v129
	v_mov_b32_e32 v54, v129
	v_mov_b32_e32 v53, v129
	v_mov_b32_e32 v52, v129
	v_mov_b32_e32 v51, v129
	v_mov_b32_e32 v50, v129
	v_mov_b32_e32 v49, v129
	v_mov_b32_e32 v48, v129
	v_mov_b32_e32 v39, v129
	v_mov_b32_e32 v38, v129
	v_mov_b32_e32 v37, v129
	v_mov_b32_e32 v36, v129
	v_mov_b32_e32 v35, v129
	v_mov_b32_e32 v34, v129
	v_mov_b32_e32 v33, v129
	v_mov_b32_e32 v32, v129
	v_mov_b32_e32 v23, v129
	v_mov_b32_e32 v22, v129
	v_mov_b32_e32 v21, v129
	v_mov_b32_e32 v20, v129
	v_mov_b32_e32 v19, v129
	v_mov_b32_e32 v18, v129
	v_mov_b32_e32 v17, v129
	v_mov_b32_e32 v16, v129
	v_mov_b32_e32 v7, v129
	v_mov_b32_e32 v6, v129
	v_mov_b32_e32 v5, v129
	v_mov_b32_e32 v4, v129
	v_mov_b32_e32 v3, v129
	v_mov_b32_e32 v2, v129
	v_mov_b32_e32 v1, v129
	v_mov_b32_e32 v0, v129
	s_branch .LBB0_478
.Lzp2_go:
	s_add_u32 s18, s18, 0x80
	s_addc_u32 s19, s19, 0
	s_add_u32 s35, s20, 0x100
	s_addc_u32 s38, s21, 0
	s_mov_b32 s20, 0
	s_add_i32 s39, s20, 2
	s_add_u32 s40, s18, 0x80
	s_addc_u32 s21, s19, 0
	s_add_i32 s51, s33, 0x100
	s_cmp_eq_u32 s47, s20
	s_cselect_b32 s21, s1, s21
	s_cselect_b32 s20, s0, s40
	v_add_u32_e32 v152, s51, v155
	s_cselect_b32 s41, s17, s38
	s_cselect_b32 s40, s16, s35
	s_add_i32 s52, s29, 0x100
	ds_read_b128 v[130:133], v152
	ds_read_b128 v[144:147], v152 offset:1024
	ds_read_b128 v[148:151], v152 offset:2048
	ds_read_b128 v[192:195], v152 offset:3072
	v_add_u32_e32 v152, s52, v155
	ds_read_b128 v[196:199], v152
	ds_read_b128 v[200:203], v152 offset:1024
	ds_read_b128 v[204:207], v152 offset:2048
	ds_read_b128 v[208:211], v152 offset:3072
	v_lshl_add_u64 v[152:153], s[18:19], 0, v[140:141]
	s_add_i32 m0, s27, 0xc000
	ds_read_b128 v[212:215], v165
	ds_read_b128 v[216:219], v165 offset:1024
	ds_read_b128 v[220:223], v165 offset:2048
	ds_read_b128 v[224:227], v165 offset:3072
	ds_read_b128 v[228:231], v165 offset:4096
	ds_read_b128 v[232:235], v165 offset:5120
	ds_read_b128 v[236:239], v165 offset:6144
	ds_read_b128 v[240:243], v165 offset:7168
	global_load_lds_dwordx4 v[152:153], off
	v_lshl_add_u64 v[152:153], s[18:19], 0, v[142:143]
	s_add_i32 m0, s27, 0xe000
	s_nop 0
	global_load_lds_dwordx4 v[152:153], off
	s_waitcnt vmcnt(8)
	s_waitcnt lgkmcnt(0)
	s_barrier
	s_setprio 1
	s_waitcnt lgkmcnt(0)
	v_mfma_f32_16x16x32_bf16 v[126:129], v[130:133], v[212:215], 0
	v_mfma_f32_16x16x32_bf16 v[122:125], v[148:151], v[212:215], 0
	v_mfma_f32_16x16x32_bf16 v[108:111], v[130:133], v[220:223], 0
	v_mfma_f32_16x16x32_bf16 v[104:107], v[148:151], v[220:223], 0
	v_mfma_f32_16x16x32_bf16 v[92:95], v[130:133], v[228:231], 0
	v_mfma_f32_16x16x32_bf16 v[88:91], v[148:151], v[228:231], 0
	v_mfma_f32_16x16x32_bf16 v[76:79], v[130:133], v[236:239], 0
	v_mfma_f32_16x16x32_bf16 v[72:75], v[148:151], v[236:239], 0
	v_mfma_f32_16x16x32_bf16 v[126:129], v[144:147], v[216:219], v[126:129]
	v_mfma_f32_16x16x32_bf16 v[122:125], v[192:195], v[216:219], v[122:125]
	v_mfma_f32_16x16x32_bf16 v[108:111], v[144:147], v[224:227], v[108:111]
	v_mfma_f32_16x16x32_bf16 v[104:107], v[192:195], v[224:227], v[104:107]
	v_mfma_f32_16x16x32_bf16 v[92:95], v[144:147], v[232:235], v[92:95]
	v_mfma_f32_16x16x32_bf16 v[88:91], v[192:195], v[232:235], v[88:91]
	v_mfma_f32_16x16x32_bf16 v[76:79], v[144:147], v[240:243], v[76:79]
	v_mfma_f32_16x16x32_bf16 v[72:75], v[192:195], v[240:243], v[72:75]
	s_setprio 0
	s_setprio 1
	v_mfma_f32_16x16x32_bf16 v[118:121], v[196:199], v[212:215], 0
	v_mfma_f32_16x16x32_bf16 v[114:117], v[204:207], v[212:215], 0
	v_mfma_f32_16x16x32_bf16 v[100:103], v[196:199], v[220:223], 0
	v_mfma_f32_16x16x32_bf16 v[96:99], v[204:207], v[220:223], 0
	v_mfma_f32_16x16x32_bf16 v[84:87], v[196:199], v[228:231], 0
	v_mfma_f32_16x16x32_bf16 v[80:83], v[204:207], v[228:231], 0
	v_mfma_f32_16x16x32_bf16 v[68:71], v[196:199], v[236:239], 0
	v_mfma_f32_16x16x32_bf16 v[64:67], v[204:207], v[236:239], 0
	v_mfma_f32_16x16x32_bf16 v[118:121], v[200:203], v[216:219], v[118:121]
	v_mfma_f32_16x16x32_bf16 v[114:117], v[208:211], v[216:219], v[114:117]
	v_mfma_f32_16x16x32_bf16 v[100:103], v[200:203], v[224:227], v[100:103]
	v_mfma_f32_16x16x32_bf16 v[96:99], v[208:211], v[224:227], v[96:99]
	v_mfma_f32_16x16x32_bf16 v[84:87], v[200:203], v[232:235], v[84:87]
	v_mfma_f32_16x16x32_bf16 v[80:83], v[208:211], v[232:235], v[80:83]
	v_mfma_f32_16x16x32_bf16 v[68:71], v[200:203], v[240:243], v[68:71]
	v_mfma_f32_16x16x32_bf16 v[64:67], v[208:211], v[240:243], v[64:67]
	s_setprio 0
	s_barrier
	s_add_i32 s51, s51, s26
	v_lshl_add_u64 v[152:153], s[40:41], 0, v[112:113]
	s_mov_b32 m0, s51
	ds_read_b128 v[212:215], v165 offset:16384
	ds_read_b128 v[216:219], v165 offset:17408
	ds_read_b128 v[220:223], v165 offset:18432
	ds_read_b128 v[224:227], v165 offset:19456
	ds_read_b128 v[228:231], v165 offset:20480
	ds_read_b128 v[232:235], v165 offset:21504
	ds_read_b128 v[236:239], v165 offset:22528
	ds_read_b128 v[240:243], v165 offset:23552
	global_load_lds_dwordx4 v[152:153], off
	s_add_i32 m0, s51, 0x2000
	v_lshl_add_u64 v[170:171], s[40:41], 0, v[134:135]
	s_add_u32 s40, s40, s2
	s_addc_u32 s41, s41, 0
	s_add_i32 s51, s52, s26
	global_load_lds_dwordx4 v[170:171], off
	v_lshl_add_u64 v[176:177], s[40:41], 0, v[112:113]
	s_mov_b32 m0, s51
	v_lshl_add_u64 v[178:179], s[40:41], 0, v[134:135]
	global_load_lds_dwordx4 v[176:177], off
	s_add_i32 m0, s51, 0x2000
	v_lshl_add_u64 v[180:181], s[20:21], 0, v[138:139]
	global_load_lds_dwordx4 v[178:179], off
	s_mov_b32 m0, s27
	v_lshl_add_u64 v[244:245], s[20:21], 0, v[136:137]
	global_load_lds_dwordx4 v[180:181], off
	s_mov_b32 m0, s42
	s_nop 0
	global_load_lds_dwordx4 v[244:245], off
	s_waitcnt vmcnt(8)
	s_waitcnt lgkmcnt(0)
	s_barrier
	s_setprio 1
	s_waitcnt lgkmcnt(0)
	v_mfma_f32_16x16x32_bf16 v[60:63], v[130:133], v[212:215], 0
	v_mfma_f32_16x16x32_bf16 v[56:59], v[148:151], v[212:215], 0
	v_mfma_f32_16x16x32_bf16 v[44:47], v[130:133], v[220:223], 0
	v_mfma_f32_16x16x32_bf16 v[40:43], v[148:151], v[220:223], 0
	v_mfma_f32_16x16x32_bf16 v[28:31], v[130:133], v[228:231], 0
	v_mfma_f32_16x16x32_bf16 v[24:27], v[148:151], v[228:231], 0
	v_mfma_f32_16x16x32_bf16 v[12:15], v[130:133], v[236:239], 0
	v_mfma_f32_16x16x32_bf16 v[8:11], v[148:151], v[236:239], 0
	v_mfma_f32_16x16x32_bf16 v[60:63], v[144:147], v[216:219], v[60:63]
	v_mfma_f32_16x16x32_bf16 v[56:59], v[192:195], v[216:219], v[56:59]
	v_mfma_f32_16x16x32_bf16 v[44:47], v[144:147], v[224:227], v[44:47]
	v_mfma_f32_16x16x32_bf16 v[40:43], v[192:195], v[224:227], v[40:43]
	v_mfma_f32_16x16x32_bf16 v[28:31], v[144:147], v[232:235], v[28:31]
	v_mfma_f32_16x16x32_bf16 v[24:27], v[192:195], v[232:235], v[24:27]
	v_mfma_f32_16x16x32_bf16 v[12:15], v[144:147], v[240:243], v[12:15]
	v_mfma_f32_16x16x32_bf16 v[8:11], v[192:195], v[240:243], v[8:11]
	s_setprio 0
	s_setprio 1
	v_mfma_f32_16x16x32_bf16 v[52:55], v[196:199], v[212:215], 0
	v_mfma_f32_16x16x32_bf16 v[48:51], v[204:207], v[212:215], 0
	v_mfma_f32_16x16x32_bf16 v[36:39], v[196:199], v[220:223], 0
	v_mfma_f32_16x16x32_bf16 v[32:35], v[204:207], v[220:223], 0
	v_mfma_f32_16x16x32_bf16 v[20:23], v[196:199], v[228:231], 0
	v_mfma_f32_16x16x32_bf16 v[16:19], v[204:207], v[228:231], 0
	v_mfma_f32_16x16x32_bf16 v[4:7], v[196:199], v[236:239], 0
	v_mfma_f32_16x16x32_bf16 v[0:3], v[204:207], v[236:239], 0
	v_mfma_f32_16x16x32_bf16 v[52:55], v[200:203], v[216:219], v[52:55]
	v_mfma_f32_16x16x32_bf16 v[48:51], v[208:211], v[216:219], v[48:51]
	v_mfma_f32_16x16x32_bf16 v[36:39], v[200:203], v[224:227], v[36:39]
	v_mfma_f32_16x16x32_bf16 v[32:35], v[208:211], v[224:227], v[32:35]
	v_mfma_f32_16x16x32_bf16 v[20:23], v[200:203], v[232:235], v[20:23]
	v_mfma_f32_16x16x32_bf16 v[16:19], v[208:211], v[232:235], v[16:19]
	v_mfma_f32_16x16x32_bf16 v[4:7], v[200:203], v[240:243], v[4:7]
	v_mfma_f32_16x16x32_bf16 v[0:3], v[208:211], v[240:243], v[0:3]
	s_setprio 0
	s_barrier
	s_add_i32 s40, s8, 0x100
	v_add_u32_e32 v191, s40, v155
	s_add_i32 s41, s9, 0x100
	ds_read_b128 v[130:133], v191
	ds_read_b128 v[144:147], v191 offset:1024
	ds_read_b128 v[148:151], v191 offset:2048
	ds_read_b128 v[192:195], v191 offset:3072
	v_add_u32_e32 v191, s41, v155
	ds_read_b128 v[196:199], v191
	ds_read_b128 v[200:203], v191 offset:1024
	ds_read_b128 v[204:207], v191 offset:2048
	ds_read_b128 v[208:211], v191 offset:3072
	s_add_u32 s20, s20, s2
	s_addc_u32 s21, s21, 0
	s_mov_b32 m0, s43
	v_lshl_add_u64 v[246:247], s[20:21], 0, v[138:139]
	ds_read_b128 v[212:215], v165 offset:32768
	ds_read_b128 v[216:219], v165 offset:33792
	ds_read_b128 v[220:223], v165 offset:34816
	ds_read_b128 v[224:227], v165 offset:35840
	ds_read_b128 v[228:231], v165 offset:36864
	ds_read_b128 v[232:235], v165 offset:37888
	ds_read_b128 v[236:239], v165 offset:38912
	ds_read_b128 v[240:243], v165 offset:39936
	global_load_lds_dwordx4 v[246:247], off
	v_lshl_add_u64 v[246:247], s[20:21], 0, v[136:137]
	s_mov_b32 m0, s44
	s_nop 0
	global_load_lds_dwordx4 v[246:247], off
	s_waitcnt vmcnt(8)
	s_waitcnt lgkmcnt(0)
	s_barrier
	s_setprio 1
	s_waitcnt lgkmcnt(0)
	v_mfma_f32_16x16x32_bf16 v[126:129], v[130:133], v[212:215], v[126:129]
	v_mfma_f32_16x16x32_bf16 v[122:125], v[148:151], v[212:215], v[122:125]
	v_mfma_f32_16x16x32_bf16 v[108:111], v[130:133], v[220:223], v[108:111]
	v_mfma_f32_16x16x32_bf16 v[104:107], v[148:151], v[220:223], v[104:107]
	v_mfma_f32_16x16x32_bf16 v[92:95], v[130:133], v[228:231], v[92:95]
	v_mfma_f32_16x16x32_bf16 v[88:91], v[148:151], v[228:231], v[88:91]
	v_mfma_f32_16x16x32_bf16 v[76:79], v[130:133], v[236:239], v[76:79]
	v_mfma_f32_16x16x32_bf16 v[72:75], v[148:151], v[236:239], v[72:75]
	v_mfma_f32_16x16x32_bf16 v[126:129], v[144:147], v[216:219], v[126:129]
	v_mfma_f32_16x16x32_bf16 v[122:125], v[192:195], v[216:219], v[122:125]
	v_mfma_f32_16x16x32_bf16 v[108:111], v[144:147], v[224:227], v[108:111]
	v_mfma_f32_16x16x32_bf16 v[104:107], v[192:195], v[224:227], v[104:107]
	v_mfma_f32_16x16x32_bf16 v[92:95], v[144:147], v[232:235], v[92:95]
	v_mfma_f32_16x16x32_bf16 v[88:91], v[192:195], v[232:235], v[88:91]
	v_mfma_f32_16x16x32_bf16 v[76:79], v[144:147], v[240:243], v[76:79]
	v_mfma_f32_16x16x32_bf16 v[72:75], v[192:195], v[240:243], v[72:75]
	s_setprio 0
	s_setprio 1
	v_mfma_f32_16x16x32_bf16 v[118:121], v[196:199], v[212:215], v[118:121]
	v_mfma_f32_16x16x32_bf16 v[114:117], v[204:207], v[212:215], v[114:117]
	v_mfma_f32_16x16x32_bf16 v[100:103], v[196:199], v[220:223], v[100:103]
	v_mfma_f32_16x16x32_bf16 v[96:99], v[204:207], v[220:223], v[96:99]
	v_mfma_f32_16x16x32_bf16 v[84:87], v[196:199], v[228:231], v[84:87]
	v_mfma_f32_16x16x32_bf16 v[80:83], v[204:207], v[228:231], v[80:83]
	v_mfma_f32_16x16x32_bf16 v[68:71], v[196:199], v[236:239], v[68:71]
	v_mfma_f32_16x16x32_bf16 v[64:67], v[204:207], v[236:239], v[64:67]
	v_mfma_f32_16x16x32_bf16 v[118:121], v[200:203], v[216:219], v[118:121]
	v_mfma_f32_16x16x32_bf16 v[114:117], v[208:211], v[216:219], v[114:117]
	v_mfma_f32_16x16x32_bf16 v[100:103], v[200:203], v[224:227], v[100:103]
	v_mfma_f32_16x16x32_bf16 v[96:99], v[208:211], v[224:227], v[96:99]
	v_mfma_f32_16x16x32_bf16 v[84:87], v[200:203], v[232:235], v[84:87]
	v_mfma_f32_16x16x32_bf16 v[80:83], v[208:211], v[232:235], v[80:83]
	v_mfma_f32_16x16x32_bf16 v[68:71], v[200:203], v[240:243], v[68:71]
	v_mfma_f32_16x16x32_bf16 v[64:67], v[208:211], v[240:243], v[64:67]
	s_setprio 0
	s_barrier
	s_add_i32 s20, s40, s26
	v_lshl_add_u64 v[152:153], v[152:153], 0, s[30:31]
	s_mov_b32 m0, s20
	ds_read_b128 v[212:215], v165 offset:49152
	ds_read_b128 v[216:219], v165 offset:50176
	ds_read_b128 v[220:223], v165 offset:51200
	ds_read_b128 v[224:227], v165 offset:52224
	ds_read_b128 v[228:231], v165 offset:53248
	ds_read_b128 v[232:235], v165 offset:54272
	ds_read_b128 v[236:239], v165 offset:55296
	ds_read_b128 v[240:243], v165 offset:56320
	global_load_lds_dwordx4 v[152:153], off
	v_lshl_add_u64 v[152:153], v[170:171], 0, s[30:31]
	s_add_i32 m0, s20, 0x2000
	s_add_i32 s20, s41, s26
	global_load_lds_dwordx4 v[152:153], off
	v_lshl_add_u64 v[152:153], v[176:177], 0, s[30:31]
	s_mov_b32 m0, s20
	s_nop 0
	global_load_lds_dwordx4 v[152:153], off
	v_lshl_add_u64 v[152:153], v[178:179], 0, s[30:31]
	s_add_i32 m0, s20, 0x2000
	s_nop 0
	global_load_lds_dwordx4 v[152:153], off
	v_lshl_add_u64 v[152:153], v[180:181], 0, s[30:31]
	s_mov_b32 m0, s45
	s_nop 0
	global_load_lds_dwordx4 v[152:153], off
	v_lshl_add_u64 v[152:153], v[244:245], 0, s[30:31]
	s_mov_b32 m0, s46
	s_nop 0
	global_load_lds_dwordx4 v[152:153], off
	s_waitcnt vmcnt(8)
	s_waitcnt lgkmcnt(0)
	s_barrier
	s_setprio 1
	s_waitcnt lgkmcnt(0)
	v_mfma_f32_16x16x32_bf16 v[60:63], v[130:133], v[212:215], v[60:63]
	v_mfma_f32_16x16x32_bf16 v[56:59], v[148:151], v[212:215], v[56:59]
	v_mfma_f32_16x16x32_bf16 v[44:47], v[130:133], v[220:223], v[44:47]
	v_mfma_f32_16x16x32_bf16 v[40:43], v[148:151], v[220:223], v[40:43]
	v_mfma_f32_16x16x32_bf16 v[28:31], v[130:133], v[228:231], v[28:31]
	v_mfma_f32_16x16x32_bf16 v[24:27], v[148:151], v[228:231], v[24:27]
	v_mfma_f32_16x16x32_bf16 v[12:15], v[130:133], v[236:239], v[12:15]
	v_mfma_f32_16x16x32_bf16 v[8:11], v[148:151], v[236:239], v[8:11]
	v_mfma_f32_16x16x32_bf16 v[60:63], v[144:147], v[216:219], v[60:63]
	v_mfma_f32_16x16x32_bf16 v[56:59], v[192:195], v[216:219], v[56:59]
	v_mfma_f32_16x16x32_bf16 v[44:47], v[144:147], v[224:227], v[44:47]
	v_mfma_f32_16x16x32_bf16 v[40:43], v[192:195], v[224:227], v[40:43]
	v_mfma_f32_16x16x32_bf16 v[28:31], v[144:147], v[232:235], v[28:31]
	v_mfma_f32_16x16x32_bf16 v[24:27], v[192:195], v[232:235], v[24:27]
	v_mfma_f32_16x16x32_bf16 v[12:15], v[144:147], v[240:243], v[12:15]
	v_mfma_f32_16x16x32_bf16 v[8:11], v[192:195], v[240:243], v[8:11]
	s_setprio 0
	s_setprio 1
	v_mfma_f32_16x16x32_bf16 v[52:55], v[196:199], v[212:215], v[52:55]
	v_mfma_f32_16x16x32_bf16 v[48:51], v[204:207], v[212:215], v[48:51]
	v_mfma_f32_16x16x32_bf16 v[36:39], v[196:199], v[220:223], v[36:39]
	v_mfma_f32_16x16x32_bf16 v[32:35], v[204:207], v[220:223], v[32:35]
	v_mfma_f32_16x16x32_bf16 v[20:23], v[196:199], v[228:231], v[20:23]
	v_mfma_f32_16x16x32_bf16 v[16:19], v[204:207], v[228:231], v[16:19]
	v_mfma_f32_16x16x32_bf16 v[4:7], v[196:199], v[236:239], v[4:7]
	v_mfma_f32_16x16x32_bf16 v[0:3], v[204:207], v[236:239], v[0:3]
	v_mfma_f32_16x16x32_bf16 v[52:55], v[200:203], v[216:219], v[52:55]
	v_mfma_f32_16x16x32_bf16 v[48:51], v[208:211], v[216:219], v[48:51]
	v_mfma_f32_16x16x32_bf16 v[36:39], v[200:203], v[224:227], v[36:39]
	v_mfma_f32_16x16x32_bf16 v[32:35], v[208:211], v[224:227], v[32:35]
	v_mfma_f32_16x16x32_bf16 v[20:23], v[200:203], v[232:235], v[20:23]
	v_mfma_f32_16x16x32_bf16 v[16:19], v[208:211], v[232:235], v[16:19]
	v_mfma_f32_16x16x32_bf16 v[4:7], v[200:203], v[240:243], v[4:7]
	v_mfma_f32_16x16x32_bf16 v[0:3], v[208:211], v[240:243], v[0:3]
	s_setprio 0
	s_barrier
	s_add_u32 s18, s18, 0x100
	s_addc_u32 s19, s19, 0
	s_add_u32 s35, s35, 0x100
	s_addc_u32 s38, s38, 0
	s_cmp_ge_u32 s39, s34
	s_mov_b32 s20, s39
	s_cbranch_scc1 .Lzp2_done

.Lzp2_done:
.LBB0_478:
	s_and_b64 vcc, exec, s[14:15]
	s_cbranch_vccz .LBB0_480
	s_barrier

.LBB0_624:
	v_mov_b32_e32 v129, 0
	s_andn2_b64 vcc, exec, s[10:11]
	s_cbranch_vccz .Lzp3_go
	v_mov_b32_e32 v128, v129
	v_mov_b32_e32 v127, v129
	v_mov_b32_e32 v126, v129
	v_mov_b32_e32 v125, v129
	v_mov_b32_e32 v124, v129
	v_mov_b32_e32 v123, v129
	v_mov_b32_e32 v122, v129
	v_mov_b32_e32 v111, v129
	v_mov_b32_e32 v110, v129
	v_mov_b32_e32 v109, v129
	v_mov_b32_e32 v108, v129
	v_mov_b32_e32 v107, v129
	v_mov_b32_e32 v106, v129
	v_mov_b32_e32 v105, v129
	v_mov_b32_e32 v104, v129
	v_mov_b32_e32 v95, v129
	v_mov_b32_e32 v94, v129
	v_mov_b32_e32 v93, v129
	v_mov_b32_e32 v92, v129
	v_mov_b32_e32 v91, v129
	v_mov_b32_e32 v90, v129
	v_mov_b32_e32 v89, v129
	v_mov_b32_e32 v88, v129
	v_mov_b32_e32 v79, v129
	v_mov_b32_e32 v78, v129
	v_mov_b32_e32 v77, v129
	v_mov_b32_e32 v76, v129
	v_mov_b32_e32 v75, v129
	v_mov_b32_e32 v74, v129
	v_mov_b32_e32 v73, v129
	v_mov_b32_e32 v72, v129
	v_mov_b32_e32 v121, v129
	v_mov_b32_e32 v120, v129
	v_mov_b32_e32 v119, v129
	v_mov_b32_e32 v118, v129
	v_mov_b32_e32 v117, v129
	v_mov_b32_e32 v116, v129
	v_mov_b32_e32 v115, v129
	v_mov_b32_e32 v114, v129
	v_mov_b32_e32 v103, v129
	v_mov_b32_e32 v102, v129
	v_mov_b32_e32 v101, v129
	v_mov_b32_e32 v100, v129
	v_mov_b32_e32 v99, v129
	v_mov_b32_e32 v98, v129
	v_mov_b32_e32 v97, v129
	v_mov_b32_e32 v96, v129
	v_mov_b32_e32 v87, v129
	v_mov_b32_e32 v86, v129
	v_mov_b32_e32 v85, v129
	v_mov_b32_e32 v84, v129
	v_mov_b32_e32 v83, v129
	v_mov_b32_e32 v82, v129
	v_mov_b32_e32 v81, v129
	v_mov_b32_e32 v80, v129
	v_mov_b32_e32 v71, v129
	v_mov_b32_e32 v70, v129
	v_mov_b32_e32 v69, v129
	v_mov_b32_e32 v68, v129
	v_mov_b32_e32 v67, v129
	v_mov_b32_e32 v66, v129
	v_mov_b32_e32 v65, v129
	v_mov_b32_e32 v64, v129
	v_mov_b32_e32 v63, v129
	v_mov_b32_e32 v62, v129
	v_mov_b32_e32 v61, v129
	v_mov_b32_e32 v60, v129
	v_mov_b32_e32 v59, v129
	v_mov_b32_e32 v58, v129
	v_mov_b32_e32 v57, v129
	v_mov_b32_e32 v56, v129
	v_mov_b32_e32 v47, v129
	v_mov_b32_e32 v46, v129
	v_mov_b32_e32 v45, v129
	v_mov_b32_e32 v44, v129
	v_mov_b32_e32 v43, v129
	v_mov_b32_e32 v42, v129
	v_mov_b32_e32 v41, v129
	v_mov_b32_e32 v40, v129
	v_mov_b32_e32 v31, v129
	v_mov_b32_e32 v30, v129
	v_mov_b32_e32 v29, v129
	v_mov_b32_e32 v28, v129
	v_mov_b32_e32 v27, v129
	v_mov_b32_e32 v26, v129
	v_mov_b32_e32 v25, v129
	v_mov_b32_e32 v24, v129
	v_mov_b32_e32 v15, v129
	v_mov_b32_e32 v14, v129
	v_mov_b32_e32 v13, v129
	v_mov_b32_e32 v12, v129
	v_mov_b32_e32 v11, v129
	v_mov_b32_e32 v10, v129
	v_mov_b32_e32 v9, v129
	v_mov_b32_e32 v8, v129
	v_mov_b32_e32 v55, v129
	v_mov_b32_e32 v54, v129
	v_mov_b32_e32 v53, v129
	v_mov_b32_e32 v52, v129
	v_mov_b32_e32 v51, v129
	v_mov_b32_e32 v50, v129
	v_mov_b32_e32 v49, v129
	v_mov_b32_e32 v48, v129
	v_mov_b32_e32 v39, v129
	v_mov_b32_e32 v38, v129
	v_mov_b32_e32 v37, v129
	v_mov_b32_e32 v36, v129
	v_mov_b32_e32 v35, v129
	v_mov_b32_e32 v34, v129
	v_mov_b32_e32 v33, v129
	v_mov_b32_e32 v32, v129
	v_mov_b32_e32 v23, v129
	v_mov_b32_e32 v22, v129
	v_mov_b32_e32 v21, v129
	v_mov_b32_e32 v20, v129
	v_mov_b32_e32 v19, v129
	v_mov_b32_e32 v18, v129
	v_mov_b32_e32 v17, v129
	v_mov_b32_e32 v16, v129
	v_mov_b32_e32 v7, v129
	v_mov_b32_e32 v6, v129
	v_mov_b32_e32 v5, v129
	v_mov_b32_e32 v4, v129
	v_mov_b32_e32 v3, v129
	v_mov_b32_e32 v2, v129
	v_mov_b32_e32 v1, v129
	v_mov_b32_e32 v0, v129
	s_branch .LBB0_627
.Lzp3_go:
	s_add_u32 s18, s18, 0x80
	s_addc_u32 s19, s19, 0
	s_add_u32 s35, s20, 0x100
	s_addc_u32 s53, s21, 0
	s_mov_b32 s20, 0
	s_add_i32 s54, s20, 2
	s_add_u32 s55, s18, 0x80
	s_addc_u32 s21, s19, 0
	s_add_i32 s58, s33, 0x100
	s_cmp_eq_u32 s45, s20
	s_cselect_b32 s21, s15, s21
	s_cselect_b32 s20, s14, s55
	v_add_u32_e32 v163, s58, v141
	s_cselect_b32 s57, s17, s53
	s_cselect_b32 s56, s16, s35
	s_add_i32 s55, s29, 0x100
	ds_read_b128 v[144:147], v163
	ds_read_b128 v[148:151], v163 offset:1024
	ds_read_b128 v[152:155], v163 offset:2048
	ds_read_b128 v[192:195], v163 offset:3072
	v_add_u32_e32 v163, s55, v141
	ds_read_b128 v[196:199], v163
	ds_read_b128 v[200:203], v163 offset:1024
	ds_read_b128 v[204:207], v163 offset:2048
	ds_read_b128 v[208:211], v163 offset:3072
	v_lshl_add_u64 v[170:171], s[18:19], 0, v[136:137]
	s_add_i32 m0, s38, 0xc000
	ds_read_b128 v[212:215], v143
	ds_read_b128 v[216:219], v143 offset:1024
	ds_read_b128 v[220:223], v143 offset:2048
	ds_read_b128 v[224:227], v143 offset:3072
	ds_read_b128 v[228:231], v143 offset:4096
	ds_read_b128 v[232:235], v143 offset:5120
	ds_read_b128 v[236:239], v143 offset:6144
	ds_read_b128 v[240:243], v143 offset:7168
	global_load_lds_dwordx4 v[170:171], off
	v_lshl_add_u64 v[170:171], s[18:19], 0, v[138:139]
	s_add_i32 m0, s38, 0xe000
	s_nop 0
	global_load_lds_dwordx4 v[170:171], off
	s_waitcnt vmcnt(8)
	s_waitcnt lgkmcnt(0)
	s_barrier
	s_setprio 1
	s_waitcnt lgkmcnt(0)
	v_mfma_f32_16x16x32_bf16 v[126:129], v[144:147], v[212:215], 0
	v_mfma_f32_16x16x32_bf16 v[122:125], v[152:155], v[212:215], 0
	v_mfma_f32_16x16x32_bf16 v[108:111], v[144:147], v[220:223], 0
	v_mfma_f32_16x16x32_bf16 v[104:107], v[152:155], v[220:223], 0
	v_mfma_f32_16x16x32_bf16 v[92:95], v[144:147], v[228:231], 0
	v_mfma_f32_16x16x32_bf16 v[88:91], v[152:155], v[228:231], 0
	v_mfma_f32_16x16x32_bf16 v[76:79], v[144:147], v[236:239], 0
	v_mfma_f32_16x16x32_bf16 v[72:75], v[152:155], v[236:239], 0
	v_mfma_f32_16x16x32_bf16 v[126:129], v[148:151], v[216:219], v[126:129]
	v_mfma_f32_16x16x32_bf16 v[122:125], v[192:195], v[216:219], v[122:125]
	v_mfma_f32_16x16x32_bf16 v[108:111], v[148:151], v[224:227], v[108:111]
	v_mfma_f32_16x16x32_bf16 v[104:107], v[192:195], v[224:227], v[104:107]
	v_mfma_f32_16x16x32_bf16 v[92:95], v[148:151], v[232:235], v[92:95]
	v_mfma_f32_16x16x32_bf16 v[88:91], v[192:195], v[232:235], v[88:91]
	v_mfma_f32_16x16x32_bf16 v[76:79], v[148:151], v[240:243], v[76:79]
	v_mfma_f32_16x16x32_bf16 v[72:75], v[192:195], v[240:243], v[72:75]
	s_setprio 0
	s_setprio 1
	v_mfma_f32_16x16x32_bf16 v[118:121], v[196:199], v[212:215], 0
	v_mfma_f32_16x16x32_bf16 v[114:117], v[204:207], v[212:215], 0
	v_mfma_f32_16x16x32_bf16 v[100:103], v[196:199], v[220:223], 0
	v_mfma_f32_16x16x32_bf16 v[96:99], v[204:207], v[220:223], 0
	v_mfma_f32_16x16x32_bf16 v[84:87], v[196:199], v[228:231], 0
	v_mfma_f32_16x16x32_bf16 v[80:83], v[204:207], v[228:231], 0
	v_mfma_f32_16x16x32_bf16 v[68:71], v[196:199], v[236:239], 0
	v_mfma_f32_16x16x32_bf16 v[64:67], v[204:207], v[236:239], 0
	v_mfma_f32_16x16x32_bf16 v[118:121], v[200:203], v[216:219], v[118:121]
	v_mfma_f32_16x16x32_bf16 v[114:117], v[208:211], v[216:219], v[114:117]
	v_mfma_f32_16x16x32_bf16 v[100:103], v[200:203], v[224:227], v[100:103]
	v_mfma_f32_16x16x32_bf16 v[96:99], v[208:211], v[224:227], v[96:99]
	v_mfma_f32_16x16x32_bf16 v[84:87], v[200:203], v[232:235], v[84:87]
	v_mfma_f32_16x16x32_bf16 v[80:83], v[208:211], v[232:235], v[80:83]
	v_mfma_f32_16x16x32_bf16 v[68:71], v[200:203], v[240:243], v[68:71]
	v_mfma_f32_16x16x32_bf16 v[64:67], v[208:211], v[240:243], v[64:67]
	s_setprio 0
	s_barrier
	s_add_i32 s58, s58, s27
	v_lshl_add_u64 v[170:171], s[56:57], 0, v[112:113]
	s_mov_b32 m0, s58
	ds_read_b128 v[212:215], v143 offset:16384
	ds_read_b128 v[216:219], v143 offset:17408
	ds_read_b128 v[220:223], v143 offset:18432
	ds_read_b128 v[224:227], v143 offset:19456
	ds_read_b128 v[228:231], v143 offset:20480
	ds_read_b128 v[232:235], v143 offset:21504
	ds_read_b128 v[236:239], v143 offset:22528
	ds_read_b128 v[240:243], v143 offset:23552
	global_load_lds_dwordx4 v[170:171], off
	s_add_i32 m0, s58, 0x2000
	v_lshl_add_u64 v[176:177], s[56:57], 0, v[130:131]
	s_add_u32 s56, s56, s2
	s_addc_u32 s57, s57, 0
	s_add_i32 s55, s55, s27
	global_load_lds_dwordx4 v[176:177], off
	v_lshl_add_u64 v[178:179], s[56:57], 0, v[112:113]
	s_mov_b32 m0, s55
	v_lshl_add_u64 v[180:181], s[56:57], 0, v[130:131]
	global_load_lds_dwordx4 v[178:179], off
	s_add_i32 m0, s55, 0x2000
	v_lshl_add_u64 v[244:245], s[20:21], 0, v[134:135]
	global_load_lds_dwordx4 v[180:181], off
	s_mov_b32 m0, s38
	v_lshl_add_u64 v[246:247], s[20:21], 0, v[132:133]
	global_load_lds_dwordx4 v[244:245], off
	s_mov_b32 m0, s39
	s_nop 0
	global_load_lds_dwordx4 v[246:247], off
	s_waitcnt vmcnt(8)
	s_waitcnt lgkmcnt(0)
	s_barrier
	s_setprio 1
	s_waitcnt lgkmcnt(0)
	v_mfma_f32_16x16x32_bf16 v[60:63], v[144:147], v[212:215], 0
	v_mfma_f32_16x16x32_bf16 v[56:59], v[152:155], v[212:215], 0
	v_mfma_f32_16x16x32_bf16 v[44:47], v[144:147], v[220:223], 0
	v_mfma_f32_16x16x32_bf16 v[40:43], v[152:155], v[220:223], 0
	v_mfma_f32_16x16x32_bf16 v[28:31], v[144:147], v[228:231], 0
	v_mfma_f32_16x16x32_bf16 v[24:27], v[152:155], v[228:231], 0
	v_mfma_f32_16x16x32_bf16 v[12:15], v[144:147], v[236:239], 0
	v_mfma_f32_16x16x32_bf16 v[8:11], v[152:155], v[236:239], 0
	v_mfma_f32_16x16x32_bf16 v[60:63], v[148:151], v[216:219], v[60:63]
	v_mfma_f32_16x16x32_bf16 v[56:59], v[192:195], v[216:219], v[56:59]
	v_mfma_f32_16x16x32_bf16 v[44:47], v[148:151], v[224:227], v[44:47]
	v_mfma_f32_16x16x32_bf16 v[40:43], v[192:195], v[224:227], v[40:43]
	v_mfma_f32_16x16x32_bf16 v[28:31], v[148:151], v[232:235], v[28:31]
	v_mfma_f32_16x16x32_bf16 v[24:27], v[192:195], v[232:235], v[24:27]
	v_mfma_f32_16x16x32_bf16 v[12:15], v[148:151], v[240:243], v[12:15]
	v_mfma_f32_16x16x32_bf16 v[8:11], v[192:195], v[240:243], v[8:11]
	s_setprio 0
	s_setprio 1
	v_mfma_f32_16x16x32_bf16 v[52:55], v[196:199], v[212:215], 0
	v_mfma_f32_16x16x32_bf16 v[48:51], v[204:207], v[212:215], 0
	v_mfma_f32_16x16x32_bf16 v[36:39], v[196:199], v[220:223], 0
	v_mfma_f32_16x16x32_bf16 v[32:35], v[204:207], v[220:223], 0
	v_mfma_f32_16x16x32_bf16 v[20:23], v[196:199], v[228:231], 0
	v_mfma_f32_16x16x32_bf16 v[16:19], v[204:207], v[228:231], 0
	v_mfma_f32_16x16x32_bf16 v[4:7], v[196:199], v[236:239], 0
	v_mfma_f32_16x16x32_bf16 v[0:3], v[204:207], v[236:239], 0
	v_mfma_f32_16x16x32_bf16 v[52:55], v[200:203], v[216:219], v[52:55]
	v_mfma_f32_16x16x32_bf16 v[48:51], v[208:211], v[216:219], v[48:51]
	v_mfma_f32_16x16x32_bf16 v[36:39], v[200:203], v[224:227], v[36:39]
	v_mfma_f32_16x16x32_bf16 v[32:35], v[208:211], v[224:227], v[32:35]
	v_mfma_f32_16x16x32_bf16 v[20:23], v[200:203], v[232:235], v[20:23]
	v_mfma_f32_16x16x32_bf16 v[16:19], v[208:211], v[232:235], v[16:19]
	v_mfma_f32_16x16x32_bf16 v[4:7], v[200:203], v[240:243], v[4:7]
	v_mfma_f32_16x16x32_bf16 v[0:3], v[208:211], v[240:243], v[0:3]
	s_setprio 0
	s_barrier
	s_add_i32 s55, s8, 0x100
	v_add_u32_e32 v163, s55, v141
	s_add_i32 s56, s9, 0x100
	ds_read_b128 v[144:147], v163
	ds_read_b128 v[148:151], v163 offset:1024
	ds_read_b128 v[152:155], v163 offset:2048
	ds_read_b128 v[192:195], v163 offset:3072
	v_add_u32_e32 v163, s56, v141
	ds_read_b128 v[196:199], v163
	ds_read_b128 v[200:203], v163 offset:1024
	ds_read_b128 v[204:207], v163 offset:2048
	ds_read_b128 v[208:211], v163 offset:3072
	s_add_u32 s20, s20, s2
	s_addc_u32 s21, s21, 0
	s_mov_b32 m0, s40
	v_lshl_add_u64 v[248:249], s[20:21], 0, v[134:135]
	ds_read_b128 v[212:215], v143 offset:32768
	ds_read_b128 v[216:219], v143 offset:33792
	ds_read_b128 v[220:223], v143 offset:34816
	ds_read_b128 v[224:227], v143 offset:35840
	ds_read_b128 v[228:231], v143 offset:36864
	ds_read_b128 v[232:235], v143 offset:37888
	ds_read_b128 v[236:239], v143 offset:38912
	ds_read_b128 v[240:243], v143 offset:39936
	global_load_lds_dwordx4 v[248:249], off
	v_lshl_add_u64 v[248:249], s[20:21], 0, v[132:133]
	s_mov_b32 m0, s41
	s_nop 0
	global_load_lds_dwordx4 v[248:249], off
	s_waitcnt vmcnt(8)
	s_waitcnt lgkmcnt(0)
	s_barrier
	s_setprio 1
	s_waitcnt lgkmcnt(0)
	v_mfma_f32_16x16x32_bf16 v[126:129], v[144:147], v[212:215], v[126:129]
	v_mfma_f32_16x16x32_bf16 v[122:125], v[152:155], v[212:215], v[122:125]
	v_mfma_f32_16x16x32_bf16 v[108:111], v[144:147], v[220:223], v[108:111]
	v_mfma_f32_16x16x32_bf16 v[104:107], v[152:155], v[220:223], v[104:107]
	v_mfma_f32_16x16x32_bf16 v[92:95], v[144:147], v[228:231], v[92:95]
	v_mfma_f32_16x16x32_bf16 v[88:91], v[152:155], v[228:231], v[88:91]
	v_mfma_f32_16x16x32_bf16 v[76:79], v[144:147], v[236:239], v[76:79]
	v_mfma_f32_16x16x32_bf16 v[72:75], v[152:155], v[236:239], v[72:75]
	v_mfma_f32_16x16x32_bf16 v[126:129], v[148:151], v[216:219], v[126:129]
	v_mfma_f32_16x16x32_bf16 v[122:125], v[192:195], v[216:219], v[122:125]
	v_mfma_f32_16x16x32_bf16 v[108:111], v[148:151], v[224:227], v[108:111]
	v_mfma_f32_16x16x32_bf16 v[104:107], v[192:195], v[224:227], v[104:107]
	v_mfma_f32_16x16x32_bf16 v[92:95], v[148:151], v[232:235], v[92:95]
	v_mfma_f32_16x16x32_bf16 v[88:91], v[192:195], v[232:235], v[88:91]
	v_mfma_f32_16x16x32_bf16 v[76:79], v[148:151], v[240:243], v[76:79]
	v_mfma_f32_16x16x32_bf16 v[72:75], v[192:195], v[240:243], v[72:75]
	s_setprio 0
	s_setprio 1
	v_mfma_f32_16x16x32_bf16 v[118:121], v[196:199], v[212:215], v[118:121]
	v_mfma_f32_16x16x32_bf16 v[114:117], v[204:207], v[212:215], v[114:117]
	v_mfma_f32_16x16x32_bf16 v[100:103], v[196:199], v[220:223], v[100:103]
	v_mfma_f32_16x16x32_bf16 v[96:99], v[204:207], v[220:223], v[96:99]
	v_mfma_f32_16x16x32_bf16 v[84:87], v[196:199], v[228:231], v[84:87]
	v_mfma_f32_16x16x32_bf16 v[80:83], v[204:207], v[228:231], v[80:83]
	v_mfma_f32_16x16x32_bf16 v[68:71], v[196:199], v[236:239], v[68:71]
	v_mfma_f32_16x16x32_bf16 v[64:67], v[204:207], v[236:239], v[64:67]
	v_mfma_f32_16x16x32_bf16 v[118:121], v[200:203], v[216:219], v[118:121]
	v_mfma_f32_16x16x32_bf16 v[114:117], v[208:211], v[216:219], v[114:117]
	v_mfma_f32_16x16x32_bf16 v[100:103], v[200:203], v[224:227], v[100:103]
	v_mfma_f32_16x16x32_bf16 v[96:99], v[208:211], v[224:227], v[96:99]
	v_mfma_f32_16x16x32_bf16 v[84:87], v[200:203], v[232:235], v[84:87]
	v_mfma_f32_16x16x32_bf16 v[80:83], v[208:211], v[232:235], v[80:83]
	v_mfma_f32_16x16x32_bf16 v[68:71], v[200:203], v[240:243], v[68:71]
	v_mfma_f32_16x16x32_bf16 v[64:67], v[208:211], v[240:243], v[64:67]
	s_setprio 0
	s_barrier
	s_add_i32 s20, s55, s27
	v_lshl_add_u64 v[170:171], v[170:171], 0, s[30:31]
	s_mov_b32 m0, s20
	ds_read_b128 v[212:215], v143 offset:49152
	ds_read_b128 v[216:219], v143 offset:50176
	ds_read_b128 v[220:223], v143 offset:51200
	ds_read_b128 v[224:227], v143 offset:52224
	ds_read_b128 v[228:231], v143 offset:53248
	ds_read_b128 v[232:235], v143 offset:54272
	ds_read_b128 v[236:239], v143 offset:55296
	ds_read_b128 v[240:243], v143 offset:56320
	global_load_lds_dwordx4 v[170:171], off
	v_lshl_add_u64 v[170:171], v[176:177], 0, s[30:31]
	s_add_i32 m0, s20, 0x2000
	s_add_i32 s20, s56, s27
	global_load_lds_dwordx4 v[170:171], off
	v_lshl_add_u64 v[170:171], v[178:179], 0, s[30:31]
	s_mov_b32 m0, s20
	s_nop 0
	global_load_lds_dwordx4 v[170:171], off
	v_lshl_add_u64 v[170:171], v[180:181], 0, s[30:31]
	s_add_i32 m0, s20, 0x2000
	s_nop 0
	global_load_lds_dwordx4 v[170:171], off
	v_lshl_add_u64 v[170:171], v[244:245], 0, s[30:31]
	s_mov_b32 m0, s42
	s_nop 0
	global_load_lds_dwordx4 v[170:171], off
	v_lshl_add_u64 v[170:171], v[246:247], 0, s[30:31]
	s_mov_b32 m0, s43
	s_nop 0
	global_load_lds_dwordx4 v[170:171], off
	s_waitcnt vmcnt(8)
	s_waitcnt lgkmcnt(0)
	s_barrier
	s_setprio 1
	s_waitcnt lgkmcnt(0)
	v_mfma_f32_16x16x32_bf16 v[60:63], v[144:147], v[212:215], v[60:63]
	v_mfma_f32_16x16x32_bf16 v[56:59], v[152:155], v[212:215], v[56:59]
	v_mfma_f32_16x16x32_bf16 v[44:47], v[144:147], v[220:223], v[44:47]
	v_mfma_f32_16x16x32_bf16 v[40:43], v[152:155], v[220:223], v[40:43]
	v_mfma_f32_16x16x32_bf16 v[28:31], v[144:147], v[228:231], v[28:31]
	v_mfma_f32_16x16x32_bf16 v[24:27], v[152:155], v[228:231], v[24:27]
	v_mfma_f32_16x16x32_bf16 v[12:15], v[144:147], v[236:239], v[12:15]
	v_mfma_f32_16x16x32_bf16 v[8:11], v[152:155], v[236:239], v[8:11]
	v_mfma_f32_16x16x32_bf16 v[60:63], v[148:151], v[216:219], v[60:63]
	v_mfma_f32_16x16x32_bf16 v[56:59], v[192:195], v[216:219], v[56:59]
	v_mfma_f32_16x16x32_bf16 v[44:47], v[148:151], v[224:227], v[44:47]
	v_mfma_f32_16x16x32_bf16 v[40:43], v[192:195], v[224:227], v[40:43]
	v_mfma_f32_16x16x32_bf16 v[28:31], v[148:151], v[232:235], v[28:31]
	v_mfma_f32_16x16x32_bf16 v[24:27], v[192:195], v[232:235], v[24:27]
	v_mfma_f32_16x16x32_bf16 v[12:15], v[148:151], v[240:243], v[12:15]
	v_mfma_f32_16x16x32_bf16 v[8:11], v[192:195], v[240:243], v[8:11]
	s_setprio 0
	s_setprio 1
	v_mfma_f32_16x16x32_bf16 v[52:55], v[196:199], v[212:215], v[52:55]
	v_mfma_f32_16x16x32_bf16 v[48:51], v[204:207], v[212:215], v[48:51]
	v_mfma_f32_16x16x32_bf16 v[36:39], v[196:199], v[220:223], v[36:39]
	v_mfma_f32_16x16x32_bf16 v[32:35], v[204:207], v[220:223], v[32:35]
	v_mfma_f32_16x16x32_bf16 v[20:23], v[196:199], v[228:231], v[20:23]
	v_mfma_f32_16x16x32_bf16 v[16:19], v[204:207], v[228:231], v[16:19]
	v_mfma_f32_16x16x32_bf16 v[4:7], v[196:199], v[236:239], v[4:7]
	v_mfma_f32_16x16x32_bf16 v[0:3], v[204:207], v[236:239], v[0:3]
	v_mfma_f32_16x16x32_bf16 v[52:55], v[200:203], v[216:219], v[52:55]
	v_mfma_f32_16x16x32_bf16 v[48:51], v[208:211], v[216:219], v[48:51]
	v_mfma_f32_16x16x32_bf16 v[36:39], v[200:203], v[224:227], v[36:39]
	v_mfma_f32_16x16x32_bf16 v[32:35], v[208:211], v[224:227], v[32:35]
	v_mfma_f32_16x16x32_bf16 v[20:23], v[200:203], v[232:235], v[20:23]
	v_mfma_f32_16x16x32_bf16 v[16:19], v[208:211], v[232:235], v[16:19]
	v_mfma_f32_16x16x32_bf16 v[4:7], v[200:203], v[240:243], v[4:7]
	v_mfma_f32_16x16x32_bf16 v[0:3], v[208:211], v[240:243], v[0:3]
	s_setprio 0
	s_barrier
	s_add_u32 s18, s18, 0x100
	s_addc_u32 s19, s19, 0
	s_add_u32 s35, s35, 0x100
	s_addc_u32 s53, s53, 0
	s_cmp_ge_u32 s54, s44
	s_mov_b32 s20, s54
	s_cbranch_scc1 .Lzp3_done

.Lzp3_done:
.LBB0_627:
	s_and_b64 vcc, exec, s[12:13]
	s_cbranch_vccz .LBB0_629
	s_barrier

.LBB0_673:
	v_readlane_b32 s38, v255, 16
	v_readlane_b32 s39, v255, 17
	s_andn2_b64 vcc, exec, s[38:39]
	s_cbranch_vccnz .LBB0_713
	s_add_u32 s20, s20, 0x80
	s_addc_u32 s21, s21, 0
	s_add_u32 s38, s22, 0x100
	s_addc_u32 s39, s23, 0
	s_mov_b32 s22, 0
	s_add_i32 s54, s22, 2
	s_add_u32 s55, s20, 0x80
	s_addc_u32 s23, s21, 0
	s_add_i32 s58, s33, 0x100
	s_cmp_eq_u32 s44, s22
	s_cselect_b32 s23, s1, s23
	s_cselect_b32 s22, s0, s55
	v_add_u32_e32 v112, s58, v147
	s_cselect_b32 s57, s19, s39
	s_cselect_b32 s56, s18, s38
	s_add_i32 s55, s29, 0x100
	ds_read_b128 v[150:153], v112
	ds_read_b128 v[190:193], v112 offset:1024
	ds_read_b128 v[194:197], v112 offset:2048
	ds_read_b128 v[198:201], v112 offset:3072
	v_add_u32_e32 v112, s55, v147
	ds_read_b128 v[202:205], v112
	ds_read_b128 v[206:209], v112 offset:1024
	ds_read_b128 v[210:213], v112 offset:2048
	ds_read_b128 v[214:217], v112 offset:3072
	v_lshl_add_u64 v[114:115], s[20:21], 0, v[140:141]
	s_add_i32 m0, s27, 0xc000
	ds_read_b128 v[218:221], v149
	ds_read_b128 v[222:225], v149 offset:1024
	ds_read_b128 v[226:229], v149 offset:2048
	ds_read_b128 v[230:233], v149 offset:3072
	ds_read_b128 v[234:237], v149 offset:4096
	ds_read_b128 v[238:241], v149 offset:5120
	ds_read_b128 v[242:245], v149 offset:6144
	ds_read_b128 v[246:249], v149 offset:7168
	global_load_lds_dwordx4 v[114:115], off
	v_lshl_add_u64 v[114:115], s[20:21], 0, v[142:143]
	s_add_i32 m0, s27, 0xe000
	s_nop 0
	global_load_lds_dwordx4 v[114:115], off
	s_waitcnt vmcnt(8)
	s_waitcnt lgkmcnt(0)
	s_barrier
	s_setprio 1
	s_waitcnt lgkmcnt(0)
	v_mfma_f32_16x16x32_bf16 v[128:131], v[150:153], v[218:221], 0
	v_mfma_f32_16x16x32_bf16 v[124:127], v[194:197], v[218:221], 0
	v_mfma_f32_16x16x32_bf16 v[108:111], v[150:153], v[226:229], 0
	v_mfma_f32_16x16x32_bf16 v[104:107], v[194:197], v[226:229], 0
	v_mfma_f32_16x16x32_bf16 v[92:95], v[150:153], v[234:237], 0
	v_mfma_f32_16x16x32_bf16 v[88:91], v[194:197], v[234:237], 0
	v_mfma_f32_16x16x32_bf16 v[76:79], v[150:153], v[242:245], 0
	v_mfma_f32_16x16x32_bf16 v[72:75], v[194:197], v[242:245], 0
	v_mfma_f32_16x16x32_bf16 v[128:131], v[190:193], v[222:225], v[128:131]
	v_mfma_f32_16x16x32_bf16 v[124:127], v[198:201], v[222:225], v[124:127]
	v_mfma_f32_16x16x32_bf16 v[108:111], v[190:193], v[230:233], v[108:111]
	v_mfma_f32_16x16x32_bf16 v[104:107], v[198:201], v[230:233], v[104:107]
	v_mfma_f32_16x16x32_bf16 v[92:95], v[190:193], v[238:241], v[92:95]
	v_mfma_f32_16x16x32_bf16 v[88:91], v[198:201], v[238:241], v[88:91]
	v_mfma_f32_16x16x32_bf16 v[76:79], v[190:193], v[246:249], v[76:79]
	v_mfma_f32_16x16x32_bf16 v[72:75], v[198:201], v[246:249], v[72:75]
	s_setprio 0
	s_setprio 1
	v_mfma_f32_16x16x32_bf16 v[120:123], v[202:205], v[218:221], 0
	v_mfma_f32_16x16x32_bf16 v[114:117], v[210:213], v[218:221], 0
	v_mfma_f32_16x16x32_bf16 v[100:103], v[202:205], v[226:229], 0
	v_mfma_f32_16x16x32_bf16 v[96:99], v[210:213], v[226:229], 0
	v_mfma_f32_16x16x32_bf16 v[84:87], v[202:205], v[234:237], 0
	v_mfma_f32_16x16x32_bf16 v[80:83], v[210:213], v[234:237], 0
	v_mfma_f32_16x16x32_bf16 v[68:71], v[202:205], v[242:245], 0
	v_mfma_f32_16x16x32_bf16 v[64:67], v[210:213], v[242:245], 0
	v_mfma_f32_16x16x32_bf16 v[120:123], v[206:209], v[222:225], v[120:123]
	v_mfma_f32_16x16x32_bf16 v[114:117], v[214:217], v[222:225], v[114:117]
	v_mfma_f32_16x16x32_bf16 v[100:103], v[206:209], v[230:233], v[100:103]
	v_mfma_f32_16x16x32_bf16 v[96:99], v[214:217], v[230:233], v[96:99]
	v_mfma_f32_16x16x32_bf16 v[84:87], v[206:209], v[238:241], v[84:87]
	v_mfma_f32_16x16x32_bf16 v[80:83], v[214:217], v[238:241], v[80:83]
	v_mfma_f32_16x16x32_bf16 v[68:71], v[206:209], v[246:249], v[68:71]
	v_mfma_f32_16x16x32_bf16 v[64:67], v[214:217], v[246:249], v[64:67]
	s_setprio 0
	s_barrier
	s_add_i32 s58, s58, s26
	v_lshl_add_u64 v[144:145], s[56:57], 0, v[134:135]
	s_mov_b32 m0, s58
	ds_read_b128 v[218:221], v149 offset:16384
	ds_read_b128 v[222:225], v149 offset:17408
	ds_read_b128 v[226:229], v149 offset:18432
	ds_read_b128 v[230:233], v149 offset:19456
	ds_read_b128 v[234:237], v149 offset:20480
	ds_read_b128 v[238:241], v149 offset:21504
	ds_read_b128 v[242:245], v149 offset:22528
	ds_read_b128 v[246:249], v149 offset:23552
	global_load_lds_dwordx4 v[144:145], off
	s_add_i32 m0, s58, 0x2000
	v_lshl_add_u64 v[154:155], s[56:57], 0, v[138:139]
	s_add_u32 s56, s56, s100
	s_addc_u32 s57, s57, 0
	s_add_i32 s55, s55, s26
	global_load_lds_dwordx4 v[154:155], off
	v_lshl_add_u64 v[170:171], s[56:57], 0, v[134:135]
	s_mov_b32 m0, s55
	v_lshl_add_u64 v[176:177], s[56:57], 0, v[138:139]
	global_load_lds_dwordx4 v[170:171], off
	s_add_i32 m0, s55, 0x2000
	v_lshl_add_u64 v[178:179], s[22:23], 0, v[132:133]
	global_load_lds_dwordx4 v[176:177], off
	s_mov_b32 m0, s27
	v_lshl_add_u64 v[180:181], s[22:23], 0, v[136:137]
	global_load_lds_dwordx4 v[178:179], off
	s_mov_b32 m0, s35
	s_nop 0
	global_load_lds_dwordx4 v[180:181], off
	s_waitcnt vmcnt(8)
	s_waitcnt lgkmcnt(0)
	s_barrier
	s_setprio 1
	s_waitcnt lgkmcnt(0)
	v_mfma_f32_16x16x32_bf16 v[60:63], v[150:153], v[218:221], 0
	v_mfma_f32_16x16x32_bf16 v[56:59], v[194:197], v[218:221], 0
	v_mfma_f32_16x16x32_bf16 v[44:47], v[150:153], v[226:229], 0
	v_mfma_f32_16x16x32_bf16 v[40:43], v[194:197], v[226:229], 0
	v_mfma_f32_16x16x32_bf16 v[28:31], v[150:153], v[234:237], 0
	v_mfma_f32_16x16x32_bf16 v[24:27], v[194:197], v[234:237], 0
	v_mfma_f32_16x16x32_bf16 v[12:15], v[150:153], v[242:245], 0
	v_mfma_f32_16x16x32_bf16 v[8:11], v[194:197], v[242:245], 0
	v_mfma_f32_16x16x32_bf16 v[60:63], v[190:193], v[222:225], v[60:63]
	v_mfma_f32_16x16x32_bf16 v[56:59], v[198:201], v[222:225], v[56:59]
	v_mfma_f32_16x16x32_bf16 v[44:47], v[190:193], v[230:233], v[44:47]
	v_mfma_f32_16x16x32_bf16 v[40:43], v[198:201], v[230:233], v[40:43]
	v_mfma_f32_16x16x32_bf16 v[28:31], v[190:193], v[238:241], v[28:31]
	v_mfma_f32_16x16x32_bf16 v[24:27], v[198:201], v[238:241], v[24:27]
	v_mfma_f32_16x16x32_bf16 v[12:15], v[190:193], v[246:249], v[12:15]
	v_mfma_f32_16x16x32_bf16 v[8:11], v[198:201], v[246:249], v[8:11]
	s_setprio 0
	s_setprio 1
	v_mfma_f32_16x16x32_bf16 v[52:55], v[202:205], v[218:221], 0
	v_mfma_f32_16x16x32_bf16 v[48:51], v[210:213], v[218:221], 0
	v_mfma_f32_16x16x32_bf16 v[36:39], v[202:205], v[226:229], 0
	v_mfma_f32_16x16x32_bf16 v[32:35], v[210:213], v[226:229], 0
	v_mfma_f32_16x16x32_bf16 v[20:23], v[202:205], v[234:237], 0
	v_mfma_f32_16x16x32_bf16 v[16:19], v[210:213], v[234:237], 0
	v_mfma_f32_16x16x32_bf16 v[4:7], v[202:205], v[242:245], 0
	v_mfma_f32_16x16x32_bf16 v[0:3], v[210:213], v[242:245], 0
	v_mfma_f32_16x16x32_bf16 v[52:55], v[206:209], v[222:225], v[52:55]
	v_mfma_f32_16x16x32_bf16 v[48:51], v[214:217], v[222:225], v[48:51]
	v_mfma_f32_16x16x32_bf16 v[36:39], v[206:209], v[230:233], v[36:39]
	v_mfma_f32_16x16x32_bf16 v[32:35], v[214:217], v[230:233], v[32:35]
	v_mfma_f32_16x16x32_bf16 v[20:23], v[206:209], v[238:241], v[20:23]
	v_mfma_f32_16x16x32_bf16 v[16:19], v[214:217], v[238:241], v[16:19]
	v_mfma_f32_16x16x32_bf16 v[4:7], v[206:209], v[246:249], v[4:7]
	v_mfma_f32_16x16x32_bf16 v[0:3], v[214:217], v[246:249], v[0:3]
	s_setprio 0
	s_barrier
	s_add_i32 s55, s8, 0x100
	v_add_u32_e32 v112, s55, v147
	s_add_i32 s56, s9, 0x100
	ds_read_b128 v[150:153], v112
	ds_read_b128 v[190:193], v112 offset:1024
	ds_read_b128 v[194:197], v112 offset:2048
	ds_read_b128 v[198:201], v112 offset:3072
	v_add_u32_e32 v112, s56, v147
	ds_read_b128 v[202:205], v112
	ds_read_b128 v[206:209], v112 offset:1024
	ds_read_b128 v[210:213], v112 offset:2048
	ds_read_b128 v[214:217], v112 offset:3072
	s_add_u32 s22, s22, s10
	s_addc_u32 s23, s23, 0
	s_mov_b32 m0, s40
	v_lshl_add_u64 v[118:119], s[22:23], 0, v[132:133]
	ds_read_b128 v[218:221], v149 offset:32768
	ds_read_b128 v[222:225], v149 offset:33792
	ds_read_b128 v[226:229], v149 offset:34816
	ds_read_b128 v[230:233], v149 offset:35840
	ds_read_b128 v[234:237], v149 offset:36864
	ds_read_b128 v[238:241], v149 offset:37888
	ds_read_b128 v[242:245], v149 offset:38912
	ds_read_b128 v[246:249], v149 offset:39936
	global_load_lds_dwordx4 v[118:119], off
	v_lshl_add_u64 v[118:119], s[22:23], 0, v[136:137]
	s_mov_b32 m0, s41
	s_nop 0
	global_load_lds_dwordx4 v[118:119], off
	s_waitcnt vmcnt(8)
	s_waitcnt lgkmcnt(0)
	s_barrier
	s_setprio 1
	s_waitcnt lgkmcnt(0)
	v_mfma_f32_16x16x32_bf16 v[128:131], v[150:153], v[218:221], v[128:131]
	v_mfma_f32_16x16x32_bf16 v[124:127], v[194:197], v[218:221], v[124:127]
	v_mfma_f32_16x16x32_bf16 v[108:111], v[150:153], v[226:229], v[108:111]
	v_mfma_f32_16x16x32_bf16 v[104:107], v[194:197], v[226:229], v[104:107]
	v_mfma_f32_16x16x32_bf16 v[92:95], v[150:153], v[234:237], v[92:95]
	v_mfma_f32_16x16x32_bf16 v[88:91], v[194:197], v[234:237], v[88:91]
	v_mfma_f32_16x16x32_bf16 v[76:79], v[150:153], v[242:245], v[76:79]
	v_mfma_f32_16x16x32_bf16 v[72:75], v[194:197], v[242:245], v[72:75]
	v_mfma_f32_16x16x32_bf16 v[128:131], v[190:193], v[222:225], v[128:131]
	v_mfma_f32_16x16x32_bf16 v[124:127], v[198:201], v[222:225], v[124:127]
	v_mfma_f32_16x16x32_bf16 v[108:111], v[190:193], v[230:233], v[108:111]
	v_mfma_f32_16x16x32_bf16 v[104:107], v[198:201], v[230:233], v[104:107]
	v_mfma_f32_16x16x32_bf16 v[92:95], v[190:193], v[238:241], v[92:95]
	v_mfma_f32_16x16x32_bf16 v[88:91], v[198:201], v[238:241], v[88:91]
	v_mfma_f32_16x16x32_bf16 v[76:79], v[190:193], v[246:249], v[76:79]
	v_mfma_f32_16x16x32_bf16 v[72:75], v[198:201], v[246:249], v[72:75]
	s_setprio 0
	s_setprio 1
	v_mfma_f32_16x16x32_bf16 v[118:121], v[202:205], v[218:221], v[120:123]
	v_mfma_f32_16x16x32_bf16 v[114:117], v[210:213], v[218:221], v[114:117]
	v_mfma_f32_16x16x32_bf16 v[100:103], v[202:205], v[226:229], v[100:103]
	v_mfma_f32_16x16x32_bf16 v[96:99], v[210:213], v[226:229], v[96:99]
	v_mfma_f32_16x16x32_bf16 v[84:87], v[202:205], v[234:237], v[84:87]
	v_mfma_f32_16x16x32_bf16 v[80:83], v[210:213], v[234:237], v[80:83]
	v_mfma_f32_16x16x32_bf16 v[68:71], v[202:205], v[242:245], v[68:71]
	v_mfma_f32_16x16x32_bf16 v[64:67], v[210:213], v[242:245], v[64:67]
	v_mfma_f32_16x16x32_bf16 v[120:123], v[206:209], v[222:225], v[118:121]
	v_mfma_f32_16x16x32_bf16 v[116:119], v[214:217], v[222:225], v[114:117]
	v_mfma_f32_16x16x32_bf16 v[100:103], v[206:209], v[230:233], v[100:103]
	v_mfma_f32_16x16x32_bf16 v[96:99], v[214:217], v[230:233], v[96:99]
	v_mfma_f32_16x16x32_bf16 v[84:87], v[206:209], v[238:241], v[84:87]
	v_mfma_f32_16x16x32_bf16 v[80:83], v[214:217], v[238:241], v[80:83]
	v_mfma_f32_16x16x32_bf16 v[68:71], v[206:209], v[246:249], v[68:71]
	v_mfma_f32_16x16x32_bf16 v[64:67], v[214:217], v[246:249], v[64:67]
	s_setprio 0
	s_barrier
	s_add_i32 s22, s55, s26
	v_lshl_add_u64 v[114:115], v[144:145], 0, s[30:31]
	s_mov_b32 m0, s22
	ds_read_b128 v[218:221], v149 offset:49152
	ds_read_b128 v[222:225], v149 offset:50176
	ds_read_b128 v[226:229], v149 offset:51200
	ds_read_b128 v[230:233], v149 offset:52224
	ds_read_b128 v[234:237], v149 offset:53248
	ds_read_b128 v[238:241], v149 offset:54272
	ds_read_b128 v[242:245], v149 offset:55296
	ds_read_b128 v[246:249], v149 offset:56320
	global_load_lds_dwordx4 v[114:115], off
	v_lshl_add_u64 v[114:115], v[154:155], 0, s[30:31]
	s_add_i32 m0, s22, 0x2000
	s_add_i32 s22, s56, s26
	global_load_lds_dwordx4 v[114:115], off
	v_lshl_add_u64 v[114:115], v[170:171], 0, s[30:31]
	s_mov_b32 m0, s22
	s_nop 0
	global_load_lds_dwordx4 v[114:115], off
	v_lshl_add_u64 v[114:115], v[176:177], 0, s[30:31]
	s_add_i32 m0, s22, 0x2000
	s_nop 0
	global_load_lds_dwordx4 v[114:115], off
	v_lshl_add_u64 v[114:115], v[178:179], 0, s[30:31]
	s_mov_b32 m0, s42
	s_nop 0
	global_load_lds_dwordx4 v[114:115], off
	v_lshl_add_u64 v[114:115], v[180:181], 0, s[30:31]
	s_mov_b32 m0, s43
	s_nop 0
	global_load_lds_dwordx4 v[114:115], off
	s_waitcnt vmcnt(8)
	s_waitcnt lgkmcnt(0)
	s_barrier
	s_setprio 1
	s_waitcnt lgkmcnt(0)
	v_mfma_f32_16x16x32_bf16 v[60:63], v[150:153], v[218:221], v[60:63]
	v_mfma_f32_16x16x32_bf16 v[56:59], v[194:197], v[218:221], v[56:59]
	v_mfma_f32_16x16x32_bf16 v[44:47], v[150:153], v[226:229], v[44:47]
	v_mfma_f32_16x16x32_bf16 v[40:43], v[194:197], v[226:229], v[40:43]
	v_mfma_f32_16x16x32_bf16 v[28:31], v[150:153], v[234:237], v[28:31]
	v_mfma_f32_16x16x32_bf16 v[24:27], v[194:197], v[234:237], v[24:27]
	v_mfma_f32_16x16x32_bf16 v[12:15], v[150:153], v[242:245], v[12:15]
	v_mfma_f32_16x16x32_bf16 v[8:11], v[194:197], v[242:245], v[8:11]
	v_mfma_f32_16x16x32_bf16 v[60:63], v[190:193], v[222:225], v[60:63]
	v_mfma_f32_16x16x32_bf16 v[56:59], v[198:201], v[222:225], v[56:59]
	v_mfma_f32_16x16x32_bf16 v[44:47], v[190:193], v[230:233], v[44:47]
	v_mfma_f32_16x16x32_bf16 v[40:43], v[198:201], v[230:233], v[40:43]
	v_mfma_f32_16x16x32_bf16 v[28:31], v[190:193], v[238:241], v[28:31]
	v_mfma_f32_16x16x32_bf16 v[24:27], v[198:201], v[238:241], v[24:27]
	v_mfma_f32_16x16x32_bf16 v[12:15], v[190:193], v[246:249], v[12:15]
	v_mfma_f32_16x16x32_bf16 v[8:11], v[198:201], v[246:249], v[8:11]
	s_setprio 0
	s_setprio 1
	v_mfma_f32_16x16x32_bf16 v[52:55], v[202:205], v[218:221], v[52:55]
	v_mfma_f32_16x16x32_bf16 v[48:51], v[210:213], v[218:221], v[48:51]
	v_mfma_f32_16x16x32_bf16 v[36:39], v[202:205], v[226:229], v[36:39]
	v_mfma_f32_16x16x32_bf16 v[32:35], v[210:213], v[226:229], v[32:35]
	v_mfma_f32_16x16x32_bf16 v[20:23], v[202:205], v[234:237], v[20:23]
	v_mfma_f32_16x16x32_bf16 v[16:19], v[210:213], v[234:237], v[16:19]
	v_mfma_f32_16x16x32_bf16 v[4:7], v[202:205], v[242:245], v[4:7]
	v_mfma_f32_16x16x32_bf16 v[0:3], v[210:213], v[242:245], v[0:3]
	v_mfma_f32_16x16x32_bf16 v[52:55], v[206:209], v[222:225], v[52:55]
	v_mfma_f32_16x16x32_bf16 v[48:51], v[214:217], v[222:225], v[48:51]
	v_mfma_f32_16x16x32_bf16 v[36:39], v[206:209], v[230:233], v[36:39]
	v_mfma_f32_16x16x32_bf16 v[32:35], v[214:217], v[230:233], v[32:35]
	v_mfma_f32_16x16x32_bf16 v[20:23], v[206:209], v[238:241], v[20:23]
	v_mfma_f32_16x16x32_bf16 v[16:19], v[214:217], v[238:241], v[16:19]
	v_mfma_f32_16x16x32_bf16 v[4:7], v[206:209], v[246:249], v[4:7]
	v_mfma_f32_16x16x32_bf16 v[0:3], v[214:217], v[246:249], v[0:3]
	s_setprio 0
	s_barrier
	s_add_u32 s20, s20, 0x100
	s_addc_u32 s21, s21, 0
	s_add_u32 s38, s38, 0x100
	s_addc_u32 s39, s39, 0
	s_cmp_ge_u32 s54, s34
	s_mov_b32 s22, s54
	s_cbranch_scc1 .Lzp1_done

.Lzp1_done:
	s_and_b64 vcc, exec, s[16:17]
	s_cbranch_vccz .LBB0_678
